# final RMSNorm phase: output stores without nt (the per-row vmcnt waits no longer include a write-through ack), on top of the plain-store input-projection epilogues
# baseline (speedup 1.0000x reference)
.LBB0_1538:
	v_lshl_add_u64 v[38:39], s[64:65], 0, v[20:21]
	v_lshl_add_u64 v[26:27], s[64:65], 0, v[18:19]
	v_add_co_u32_e32 v52, vcc, 0x200000, v38
	v_lshl_add_u64 v[50:51], v[38:39], 0, s[10:11]
	v_add_co_u32_e64 v54, s[0:1], s13, v26
	v_addc_co_u32_e32 v53, vcc, 0, v39, vcc
	s_nop 0
	v_addc_co_u32_e64 v55, s[0:1], 0, v27, s[0:1]
	global_load_dwordx4 v[26:29], v[50:51], off offset:16
	global_load_dwordx4 v[30:33], v[50:51], off offset:32
	global_load_dwordx4 v[34:37], v[54:55], off nt
	global_load_dwordx4 v[38:41], v[52:53], off
	global_load_dwordx4 v[42:45], v[50:51], off offset:48
	global_load_dwordx4 v[46:49], v[54:55], off offset:1024 nt
	v_add_u32_e32 v16, s46, v16
	v_cmp_lt_i32_e64 s[0:1], s14, v16
	s_or_b64 s[8:9], s[0:1], s[8:9]
	v_lshl_add_u64 v[18:19], v[18:19], 0, s[2:3]
	v_lshl_add_u64 v[20:21], v[20:21], 0, s[4:5]
	s_waitcnt vmcnt(5)
	v_mov_b32_e32 v50, v27
	v_mov_b32_e32 v51, v28
	v_mov_b32_e32 v27, v29
	s_waitcnt vmcnt(2)
	v_mov_b32_e32 v58, v39
	v_mov_b32_e32 v59, v40
	v_mov_b32_e32 v39, v41
	v_add_f32_e32 v28, v30, v31
	v_add_f32_e32 v30, v32, v33
	v_pk_add_f32 v[26:27], v[50:51], v[26:27]
	s_waitcnt vmcnt(1)
	v_mov_b32_e32 v29, v44
	v_mov_b32_e32 v31, v45
	v_pk_add_f32 v[38:39], v[58:59], v[38:39]
	v_pk_add_f32 v[26:27], v[26:27], v[26:27] op_sel:[0,1] op_sel_hi:[1,0]
	v_pk_add_f32 v[28:29], v[28:29], v[30:31]
	v_pk_add_f32 v[30:31], v[38:39], v[38:39] op_sel:[0,1] op_sel_hi:[1,0]
	v_mov_b32_e32 v27, v43
	v_mov_b32_e32 v31, v42
	v_pk_add_f32 v[26:27], v[30:31], v[26:27]
	v_lshlrev_b32_e32 v32, 16, v34
	v_pk_add_f32 v[26:27], v[26:27], v[28:29]
	v_and_b32_e32 v33, 0xffff0000, v34
	v_add_f32_e32 v25, v26, v27
	v_fmamk_f32 v25, v25, 0x3a800000, v17
	v_mul_f32_e32 v26, 0x4f800000, v25
	v_cmp_gt_f32_e32 vcc, s12, v25
	v_lshlrev_b32_e32 v34, 16, v35
	v_and_b32_e32 v35, 0xffff0000, v35
	v_cndmask_b32_e32 v25, v25, v26, vcc
	v_sqrt_f32_e32 v26, v25
	v_lshlrev_b32_e32 v52, 16, v36
	v_and_b32_e32 v53, 0xffff0000, v36
	v_lshlrev_b32_e32 v36, 16, v37
	v_add_u32_e32 v27, -1, v26
	v_add_u32_e32 v28, 1, v26
	v_fma_f32 v29, -v27, v26, v25
	v_fma_f32 v30, -v28, v26, v25
	v_cmp_ge_f32_e64 s[0:1], 0, v29
	v_and_b32_e32 v37, 0xffff0000, v37
	s_waitcnt vmcnt(0)
	v_lshlrev_b32_e32 v54, 16, v46
	v_cndmask_b32_e64 v26, v26, v27, s[0:1]
	v_cmp_lt_f32_e64 s[0:1], 0, v30
	v_and_b32_e32 v55, 0xffff0000, v46
	v_lshlrev_b32_e32 v46, 16, v47
	v_cndmask_b32_e64 v26, v26, v28, s[0:1]
	v_mul_f32_e32 v27, 0x37800000, v26
	v_cndmask_b32_e32 v26, v26, v27, vcc
	v_cmp_class_f32_e32 vcc, v25, v24
	v_and_b32_e32 v47, 0xffff0000, v47
	v_lshlrev_b32_e32 v56, 16, v48
	v_cndmask_b32_e32 v25, v26, v25, vcc
	v_div_scale_f32 v26, s[0:1], v25, v25, 1.0
	v_rcp_f32_e32 v28, v26
	v_div_scale_f32 v27, vcc, 1.0, v25, 1.0
	v_and_b32_e32 v57, 0xffff0000, v48
	v_fma_f32 v29, -v26, v28, 1.0
	v_fmac_f32_e32 v28, v29, v28
	v_mul_f32_e32 v29, v27, v28
	v_fma_f32 v30, -v26, v29, v27
	v_fmac_f32_e32 v29, v30, v28
	v_fma_f32 v26, -v26, v29, v27
	v_div_fmas_f32 v26, v26, v28, v29
	v_div_fixup_f32 v26, v26, v25, 1.0
	v_lshlrev_b32_e32 v48, 16, v49
	v_and_b32_e32 v49, 0xffff0000, v49
	v_pk_mul_f32 v[30:31], v[26:27], v[32:33] op_sel_hi:[0,1]
	v_pk_mul_f32 v[28:29], v[26:27], v[34:35] op_sel_hi:[0,1]
	v_pk_mul_f32 v[34:35], v[26:27], v[52:53] op_sel_hi:[0,1]
	v_pk_mul_f32 v[32:33], v[26:27], v[36:37] op_sel_hi:[0,1]
	v_pk_mul_f32 v[38:39], v[26:27], v[54:55] op_sel_hi:[0,1]
	v_pk_mul_f32 v[36:37], v[26:27], v[46:47] op_sel_hi:[0,1]
	v_pk_mul_f32 v[42:43], v[26:27], v[56:57] op_sel_hi:[0,1]
	v_pk_mul_f32 v[40:41], v[26:27], v[48:49] op_sel_hi:[0,1]
	v_pk_mul_f32 v[28:29], v[6:7], v[28:29]
	v_pk_mul_f32 v[26:27], v[4:5], v[30:31]
	v_pk_mul_f32 v[32:33], v[2:3], v[32:33]
	v_pk_mul_f32 v[30:31], v[0:1], v[34:35]
	v_pk_mul_f32 v[36:37], v[14:15], v[36:37]
	v_pk_mul_f32 v[34:35], v[12:13], v[38:39]
	v_pk_mul_f32 v[40:41], v[10:11], v[40:41]
	v_pk_mul_f32 v[38:39], v[8:9], v[42:43]
	global_store_dwordx4 v[22:23], v[26:29], off offset:-2064
	global_store_dwordx4 v[22:23], v[30:33], off offset:-2048
	global_store_dwordx4 v[22:23], v[34:37], off offset:-16
	global_store_dwordx4 v[22:23], v[38:41], off
	v_lshl_add_u64 v[22:23], v[22:23], 0, s[6:7]
	s_andn2_b64 exec, exec, s[8:9]
	s_cbranch_execnz .LBB0_1538
